# norm phase: counted vmcnt waits (no store-ack drains), ctx split-K partial loads issued together; plus prologue load batching
# speedup vs baseline: 1.0206x; 1.0109x over previous
; __device__ __forceinline__ void norm_phase(const Args& a, LAS unsigned char* lds, int l, int j, int l2, int j2, int nrows, float wgt, int tid, int G) {
;     ...
;     for (int ri = 0; ri < nmine; ++ri) {
;     ...
;         zc0 = zn0; zc1 = zn1; qc0 = qn0; qc1 = qn1;
; #pragma unroll
;         for (int k = 0; k < 4; ++k) xc[k] = xn[k];
;     }
.LBB0_556:
	s_add_i32 s3, s3, 1
	v_add_u32_e32 v58, s3, v162
	s_movk_i32 s14, 0xc001
	v_cmp_eq_u32_e32 vcc, s14, v58
	s_waitcnt vmcnt(5)
	v_mov_b64_e32 v[60:61], v[48:49]
	s_waitcnt vmcnt(4)
	v_mov_b64_e32 v[68:69], v[56:57]
	v_mov_b64_e32 v[64:65], v[32:33]
	v_mov_b64_e32 v[72:73], v[40:41]
	v_mov_b64_e32 v[112:113], v[20:21]
	v_mov_b64_e32 v[108:109], v[28:29]
	v_mov_b64_e32 v[104:105], v[36:37]
	v_mov_b64_e32 v[100:101], v[44:45]
	s_or_b64 s[30:31], vcc, s[30:31]
	v_mov_b64_e32 v[58:59], v[46:47]
	v_mov_b64_e32 v[66:67], v[54:55]
	v_mov_b64_e32 v[62:63], v[30:31]
	v_mov_b64_e32 v[70:71], v[38:39]
	v_mov_b32_e32 v116, v148
	v_mov_b64_e32 v[110:111], v[18:19]
	v_mov_b64_e32 v[106:107], v[26:27]
	v_mov_b64_e32 v[102:103], v[34:35]
	v_mov_b64_e32 v[98:99], v[42:43]
	s_andn2_b64 exec, exec, s[30:31]
	s_cbranch_execz .LBB0_581

; __device__ __forceinline__ void norm_phase(const Args& a, LAS unsigned char* lds, int l, int j, int l2, int j2, int nrows, float wgt, int tid, int G) {
;     ...
;         if (m != mcur) {
;             mcur = m;
;             if (l >= 0) {
;                 const float* gate = MOD + ((size_t)l * 9 + m) * 9216 + (3 * j + 2) * DM;
;                 const float* post = a.in[I_NPOST] + (size_t)(l * 3 + j) * DM;
; #pragma unroll
;                 for (int k = 0; k < 4; ++k) { const int c = 512 * (k >> 1) + cl + 4 * (k & 1); Av[k] = *(const f32x4*)(gate + c) * *(const f32x4*)(post + c) * wgt; }
;             }
;             if (l2 < DEPTH) {
;                 const float* shift = MOD + ((size_t)l2 * 9 + m) * 9216 + (3 * j2) * DM;
;                 const float* scale = shift + DM;
;                 const float* pre = a.in[I_NPRE] + (size_t)(l2 * 3 + j2) * DM;
; #pragma unroll
;                 for (int k = 0; k < 4; ++k) { const int c = 512 * (k >> 1) + cl + 4 * (k & 1); Bv[k] = *(const f32x4*)(pre + c) * (*(const f32x4*)(scale + c) + 1.0f); Cv[k] = *(const f32x4*)(shift + c); }
;             }
;         }
;         f32x4 sv[4];
;         if (l < 0) {
; #pragma unroll
;             for (int k = 0; k < 4; ++k) sv[k] = xc[k];
;         } else {
;             unpack8(qc0, sv[0], sv[1]); unpack8(qc1, sv[2], sv[3]);
;             f32x4 zv[4];
;             unpack8(zc0, zv[0], zv[1]); unpack8(zc1, zv[2], zv[3]);
;             if (!lat) {
; #pragma unroll
;                 for (int pp = 1; pp < 8; ++pp) { const bf16_t* zp = Z + (size_t)(row + pp * T_CTX) * DM + cl; f32x4 t0, t1, t2, t3;
;                     unpack8(*(const u32x4*)zp, t0, t1); unpack8(*(const u32x4*)(zp + 512), t2, t3); zv[0] += t0; zv[1] += t1; zv[2] += t2; zv[3] += t3; }
.LBB0_567:
	s_andn2_b64 vcc, exec, s[10:11]
	s_cbranch_vccnz .LBB0_569
	s_waitcnt lgkmcnt(9)
	v_lshl_add_u64 v[2:3], s[24:25], 0, v[148:149]
	v_mov_b64_e32 v[4:5], s[28:29]
	s_waitcnt lgkmcnt(7)
	v_mad_u64_u32 v[14:15], s[14:15], v2, s59, v[4:5]
	v_mov_b32_e32 v2, v15
	v_mad_u64_u32 v[2:3], s[14:15], v3, s59, v[2:3]
	v_mov_b32_e32 v15, v2
	s_mov_b64 s[14:15], 0x1000
	s_waitcnt lgkmcnt(0)
	v_lshl_add_u64 v[78:79], v[14:15], 0, s[14:15]
	v_lshl_add_u64 v[10:11], v[78:79], 0, v[0:1]
	global_load_dwordx4 v[50:53], v[142:143], off offset:16
	global_load_dwordx4 v[2:5], v[142:143], off
	v_mov_b32_e32 v117, v1
	global_load_dwordx4 v[10:13], v[10:11], off
	v_lshl_add_u64 v[90:91], v[14:15], 0, v[0:1]
	v_lshl_add_u64 v[74:75], v[78:79], 0, v[116:117]
	v_mov_b32_e32 v115, v1
	v_lshl_add_u64 v[78:79], v[78:79], 0, v[114:115]
	s_waitcnt vmcnt(0)
	v_pk_add_f32 v[12:13], v[12:13], 1.0 op_sel_hi:[1,0]
	v_pk_add_f32 v[10:11], v[10:11], 1.0 op_sel_hi:[1,0]
	v_pk_mul_f32 v[4:5], v[4:5], v[12:13]
	v_pk_mul_f32 v[2:3], v[2:3], v[10:11]
	global_load_dwordx4 v[10:13], v[90:91], off offset:16
	global_load_dwordx4 v[14:17], v[90:91], off
	s_nop 0
	global_load_dwordx4 v[74:77], v[74:75], off
	s_waitcnt vmcnt(0)
	v_pk_add_f32 v[76:77], v[76:77], 1.0 op_sel_hi:[1,0]
	v_pk_add_f32 v[74:75], v[74:75], 1.0 op_sel_hi:[1,0]
	v_pk_mul_f32 v[52:53], v[52:53], v[76:77]
	v_pk_mul_f32 v[50:51], v[50:51], v[74:75]
	global_load_dwordx4 v[94:97], v[142:143], off offset:2064
	global_load_dwordx4 v[74:77], v[142:143], off offset:2048
	global_load_dwordx4 v[114:117], v[78:79], off offset:16
	s_nop 0
	global_load_dwordx4 v[78:81], v[78:79], off
	s_waitcnt vmcnt(1)
	v_pk_add_f32 v[116:117], v[116:117], 1.0 op_sel_hi:[1,0]
	s_waitcnt vmcnt(0)
	v_pk_add_f32 v[80:81], v[80:81], 1.0 op_sel_hi:[1,0]
	v_pk_add_f32 v[78:79], v[78:79], 1.0 op_sel_hi:[1,0]
	v_pk_mul_f32 v[76:77], v[76:77], v[80:81]
	v_pk_mul_f32 v[74:75], v[74:75], v[78:79]
	global_load_dwordx4 v[78:81], v[90:91], off offset:2064
	s_nop 0
	global_load_dwordx4 v[90:93], v[90:91], off offset:2048
	s_waitcnt vmcnt(0)
	v_pk_add_f32 v[114:115], v[114:115], 1.0 op_sel_hi:[1,0]
	v_pk_mul_f32 v[96:97], v[96:97], v[116:117]
	v_pk_mul_f32 v[94:95], v[94:95], v[114:115]
.LBB0_569:
	s_or_b64 exec, exec, s[18:19]
	s_mov_b64 s[18:19], -1
	s_and_b64 vcc, exec, s[8:9]
	s_cbranch_vccz .LBB0_576
	s_movk_i32 s14, 0x3fff
	v_cmp_lt_i32_e32 vcc, s14, v150
	v_lshlrev_b32_e32 v152, 16, v110
	v_and_b32_e32 v153, 0xffff0000, v110
	v_lshlrev_b32_e32 v156, 16, v111
	v_and_b32_e32 v157, 0xffff0000, v111
	v_lshlrev_b32_e32 v116, 16, v112
	v_and_b32_e32 v117, 0xffff0000, v112
	v_lshlrev_b32_e32 v124, 16, v113
	v_and_b32_e32 v125, 0xffff0000, v113
	v_lshlrev_b32_e32 v122, 16, v106
	v_and_b32_e32 v123, 0xffff0000, v106
	v_lshlrev_b32_e32 v120, 16, v107
	v_and_b32_e32 v121, 0xffff0000, v107
	v_lshlrev_b32_e32 v110, 16, v108
	v_and_b32_e32 v111, 0xffff0000, v108
	v_lshlrev_b32_e32 v106, 16, v109
	v_and_b32_e32 v107, 0xffff0000, v109
	s_and_saveexec_b64 s[18:19], vcc
	s_cbranch_execz .LBB0_572
	v_add_u32_e32 v108, 0x47ff, v151
	v_mov_b32_e32 v109, v1
	v_lshlrev_b64 v[108:109], 11, v[108:109]
	v_lshl_add_u64 v[108:109], v[132:133], 0, v[108:109]
	global_load_dwordx4 v[208:211], v[108:109], off
	global_load_dwordx4 v[212:215], v[108:109], off offset:1024
	v_add_u32_e32 v108, 0x4fff, v151
	v_mov_b32_e32 v109, v1
	v_lshlrev_b64 v[108:109], 11, v[108:109]
	v_lshl_add_u64 v[108:109], v[132:133], 0, v[108:109]
	global_load_dwordx4 v[216:219], v[108:109], off
	global_load_dwordx4 v[220:223], v[108:109], off offset:1024
	v_add_u32_e32 v108, 0x57ff, v151
	v_mov_b32_e32 v109, v1
	v_lshlrev_b64 v[108:109], 11, v[108:109]
	v_lshl_add_u64 v[108:109], v[132:133], 0, v[108:109]
	global_load_dwordx4 v[224:227], v[108:109], off
	global_load_dwordx4 v[228:231], v[108:109], off offset:1024
	v_add_u32_e32 v108, 0x5fff, v151
	v_mov_b32_e32 v109, v1
	v_lshlrev_b64 v[108:109], 11, v[108:109]
	v_lshl_add_u64 v[108:109], v[132:133], 0, v[108:109]
	global_load_dwordx4 v[232:235], v[108:109], off
	global_load_dwordx4 v[236:239], v[108:109], off offset:1024
	v_add_u32_e32 v108, 0x67ff, v151
	v_mov_b32_e32 v109, v1
	v_lshlrev_b64 v[108:109], 11, v[108:109]
	v_lshl_add_u64 v[108:109], v[132:133], 0, v[108:109]
	global_load_dwordx4 v[240:243], v[108:109], off
	global_load_dwordx4 v[244:247], v[108:109], off offset:1024
	v_add_u32_e32 v108, 0x6fff, v151
	v_mov_b32_e32 v109, v1
	v_lshlrev_b64 v[108:109], 11, v[108:109]
	v_lshl_add_u64 v[108:109], v[132:133], 0, v[108:109]
	global_load_dwordx4 v[248:251], v[108:109], off
	global_load_dwordx4 v[172:175], v[108:109], off offset:1024
	v_add_u32_e32 v108, 0x77ff, v151
	v_mov_b32_e32 v109, v1
	v_lshlrev_b64 v[108:109], 11, v[108:109]
	v_lshl_add_u64 v[108:109], v[132:133], 0, v[108:109]
	global_load_dwordx4 v[176:179], v[108:109], off
	global_load_dwordx4 v[180:183], v[108:109], off offset:1024
	v_add_u32_e32 v108, 0x47ff, v151
	v_mov_b32_e32 v109, v1
	v_lshlrev_b64 v[108:109], 11, v[108:109]
	v_lshl_add_u64 v[108:109], v[132:133], 0, v[108:109]
	s_waitcnt vmcnt(13)
	v_mov_b64_e32 v[112:113], v[208:209]
	v_mov_b64_e32 v[114:115], v[210:211]
	s_nop 0
	v_lshlrev_b32_e32 v118, 16, v112
	v_and_b32_e32 v119, 0xffff0000, v112
	v_lshlrev_b32_e32 v126, 16, v113
	v_and_b32_e32 v127, 0xffff0000, v113
	v_lshlrev_b32_e32 v154, 16, v114
	v_and_b32_e32 v155, 0xffff0000, v114
	v_lshlrev_b32_e32 v164, 16, v115
	v_and_b32_e32 v165, 0xffff0000, v115
	s_waitcnt vmcnt(12)
; __device__ __forceinline__ void norm_phase(const Args& a, LAS unsigned char* lds, int l, int j, int l2, int j2, int nrows, float wgt, int tid, int G) {
;     ...
;             if (!lat) {
; #pragma unroll
;                 for (int pp = 1; pp < 8; ++pp) { const bf16_t* zp = Z + (size_t)(row + pp * T_CTX) * DM + cl; f32x4 t0, t1, t2, t3;
;                     unpack8(*(const u32x4*)zp, t0, t1); unpack8(*(const u32x4*)(zp + 512), t2, t3); zv[0] += t0; zv[1] += t1; zv[2] += t2; zv[3] += t3; }
	v_mov_b64_e32 v[112:113], v[212:213]
	v_mov_b64_e32 v[114:115], v[214:215]
	v_pk_add_f32 v[126:127], v[156:157], v[126:127]
	v_pk_add_f32 v[118:119], v[152:153], v[118:119]
	v_pk_add_f32 v[124:125], v[124:125], v[164:165]
	v_pk_add_f32 v[116:117], v[116:117], v[154:155]
	s_nop 0
	v_lshlrev_b32_e32 v166, 16, v114
	v_and_b32_e32 v167, 0xffff0000, v114
	v_lshlrev_b32_e32 v114, 16, v115
	v_and_b32_e32 v115, 0xffff0000, v115
	v_pk_add_f32 v[114:115], v[106:107], v[114:115]
	v_add_u32_e32 v106, 0x4fff, v151
	v_mov_b32_e32 v107, v1
	v_lshlrev_b32_e32 v108, 16, v112
	v_and_b32_e32 v109, 0xffff0000, v112
	v_lshlrev_b32_e32 v112, 16, v113
	v_and_b32_e32 v113, 0xffff0000, v113
	v_lshlrev_b64 v[106:107], 11, v[106:107]
	v_pk_add_f32 v[112:113], v[120:121], v[112:113]
	v_pk_add_f32 v[120:121], v[122:123], v[108:109]
	v_lshl_add_u64 v[122:123], v[132:133], 0, v[106:107]
	s_waitcnt vmcnt(11)
	v_mov_b64_e32 v[106:107], v[216:217]
	v_mov_b64_e32 v[108:109], v[218:219]
	v_pk_add_f32 v[110:111], v[110:111], v[166:167]
	s_nop 0
	v_lshlrev_b32_e32 v152, 16, v106
	v_and_b32_e32 v153, 0xffff0000, v106
	v_lshlrev_b32_e32 v154, 16, v107
	v_and_b32_e32 v155, 0xffff0000, v107
	v_lshlrev_b32_e32 v156, 16, v108
	v_and_b32_e32 v157, 0xffff0000, v108
	v_lshlrev_b32_e32 v164, 16, v109
	v_and_b32_e32 v165, 0xffff0000, v109
	s_waitcnt vmcnt(10)
	v_mov_b64_e32 v[106:107], v[220:221]
	v_mov_b64_e32 v[108:109], v[222:223]
	v_pk_add_f32 v[118:119], v[118:119], v[152:153]
	v_pk_add_f32 v[126:127], v[126:127], v[154:155]
	v_pk_add_f32 v[116:117], v[116:117], v[156:157]
	v_pk_add_f32 v[124:125], v[124:125], v[164:165]
	s_nop 0
	v_lshlrev_b32_e32 v122, 16, v106
	v_and_b32_e32 v123, 0xffff0000, v106
	v_lshlrev_b32_e32 v106, 16, v107
	v_and_b32_e32 v107, 0xffff0000, v107
	v_pk_add_f32 v[112:113], v[112:113], v[106:107]
	v_add_u32_e32 v106, 0x57ff, v151
	v_mov_b32_e32 v107, v1
	v_lshlrev_b64 v[106:107], 11, v[106:107]
	v_lshlrev_b32_e32 v166, 16, v108
	v_and_b32_e32 v167, 0xffff0000, v108
	v_lshlrev_b32_e32 v108, 16, v109
	v_and_b32_e32 v109, 0xffff0000, v109
	v_pk_add_f32 v[120:121], v[120:121], v[122:123]
	v_lshl_add_u64 v[122:123], v[132:133], 0, v[106:107]
	v_pk_add_f32 v[114:115], v[114:115], v[108:109]
	s_waitcnt vmcnt(9)
	v_mov_b64_e32 v[106:107], v[224:225]
	v_mov_b64_e32 v[108:109], v[226:227]
	v_pk_add_f32 v[110:111], v[110:111], v[166:167]
	s_nop 0
	v_lshlrev_b32_e32 v152, 16, v106
	v_and_b32_e32 v153, 0xffff0000, v106
	v_lshlrev_b32_e32 v154, 16, v107
	v_and_b32_e32 v155, 0xffff0000, v107
	v_lshlrev_b32_e32 v156, 16, v108
	v_and_b32_e32 v157, 0xffff0000, v108
	v_lshlrev_b32_e32 v164, 16, v109
	v_and_b32_e32 v165, 0xffff0000, v109
	s_waitcnt vmcnt(8)
	v_mov_b64_e32 v[106:107], v[228:229]
	v_mov_b64_e32 v[108:109], v[230:231]
	v_pk_add_f32 v[126:127], v[126:127], v[154:155]
	v_pk_add_f32 v[118:119], v[118:119], v[152:153]
	v_pk_add_f32 v[124:125], v[124:125], v[164:165]
	v_pk_add_f32 v[116:117], v[116:117], v[156:157]
	s_nop 0
	v_lshlrev_b32_e32 v122, 16, v106
	v_and_b32_e32 v123, 0xffff0000, v106
	v_lshlrev_b32_e32 v106, 16, v107
	v_and_b32_e32 v107, 0xffff0000, v107
	v_pk_add_f32 v[112:113], v[112:113], v[106:107]
	v_add_u32_e32 v106, 0x5fff, v151
	v_mov_b32_e32 v107, v1
	v_lshlrev_b64 v[106:107], 11, v[106:107]
	v_lshlrev_b32_e32 v166, 16, v108
	v_and_b32_e32 v167, 0xffff0000, v108
	v_lshlrev_b32_e32 v108, 16, v109
	v_and_b32_e32 v109, 0xffff0000, v109
	v_pk_add_f32 v[120:121], v[120:121], v[122:123]
	v_lshl_add_u64 v[122:123], v[132:133], 0, v[106:107]
	v_pk_add_f32 v[114:115], v[114:115], v[108:109]
	s_waitcnt vmcnt(7)
	v_mov_b64_e32 v[106:107], v[232:233]
	v_mov_b64_e32 v[108:109], v[234:235]
	v_pk_add_f32 v[110:111], v[110:111], v[166:167]
	s_nop 0
	v_lshlrev_b32_e32 v152, 16, v106
	v_and_b32_e32 v153, 0xffff0000, v106
	v_lshlrev_b32_e32 v154, 16, v107
	v_and_b32_e32 v155, 0xffff0000, v107
	v_lshlrev_b32_e32 v156, 16, v108
	v_and_b32_e32 v157, 0xffff0000, v108
	v_lshlrev_b32_e32 v164, 16, v109
	v_and_b32_e32 v165, 0xffff0000, v109
	s_waitcnt vmcnt(6)
; __device__ __forceinline__ void norm_phase(const Args& a, LAS unsigned char* lds, int l, int j, int l2, int j2, int nrows, float wgt, int tid, int G) {
;     ...
;             if (!lat) {
; #pragma unroll
;                 for (int pp = 1; pp < 8; ++pp) { const bf16_t* zp = Z + (size_t)(row + pp * T_CTX) * DM + cl; f32x4 t0, t1, t2, t3;
;                     unpack8(*(const u32x4*)zp, t0, t1); unpack8(*(const u32x4*)(zp + 512), t2, t3); zv[0] += t0; zv[1] += t1; zv[2] += t2; zv[3] += t3; }
;             }
	v_mov_b64_e32 v[106:107], v[236:237]
	v_mov_b64_e32 v[108:109], v[238:239]
	v_pk_add_f32 v[118:119], v[118:119], v[152:153]
	v_pk_add_f32 v[126:127], v[126:127], v[154:155]
	v_pk_add_f32 v[116:117], v[116:117], v[156:157]
	v_pk_add_f32 v[124:125], v[124:125], v[164:165]
	s_nop 0
	v_lshlrev_b32_e32 v122, 16, v106
	v_and_b32_e32 v123, 0xffff0000, v106
	v_lshlrev_b32_e32 v106, 16, v107
	v_and_b32_e32 v107, 0xffff0000, v107
	v_pk_add_f32 v[120:121], v[120:121], v[122:123]
	v_pk_add_f32 v[122:123], v[112:113], v[106:107]
	v_add_u32_e32 v106, 0x67ff, v151
	v_mov_b32_e32 v107, v1
	v_lshlrev_b32_e32 v166, 16, v108
	v_and_b32_e32 v167, 0xffff0000, v108
	v_lshlrev_b64 v[106:107], 11, v[106:107]
	v_lshlrev_b32_e32 v108, 16, v109
	v_and_b32_e32 v109, 0xffff0000, v109
	v_pk_add_f32 v[152:153], v[110:111], v[166:167]
	v_lshl_add_u64 v[110:111], v[132:133], 0, v[106:107]
	v_pk_add_f32 v[114:115], v[114:115], v[108:109]
	s_waitcnt vmcnt(5)
	v_mov_b64_e32 v[106:107], v[240:241]
	v_mov_b64_e32 v[108:109], v[242:243]
	s_nop 0
	v_lshlrev_b32_e32 v112, 16, v106
	v_and_b32_e32 v113, 0xffff0000, v106
	v_lshlrev_b32_e32 v154, 16, v107
	v_and_b32_e32 v155, 0xffff0000, v107
	v_lshlrev_b32_e32 v156, 16, v108
	v_and_b32_e32 v157, 0xffff0000, v108
	v_lshlrev_b32_e32 v164, 16, v109
	v_and_b32_e32 v165, 0xffff0000, v109
	s_waitcnt vmcnt(4)
	v_mov_b64_e32 v[106:107], v[244:245]
	v_mov_b64_e32 v[108:109], v[246:247]
	v_pk_add_f32 v[112:113], v[118:119], v[112:113]
	v_pk_add_f32 v[116:117], v[116:117], v[156:157]
	s_nop 0
	v_lshlrev_b32_e32 v166, 16, v106
	v_and_b32_e32 v167, 0xffff0000, v106
	v_pk_add_f32 v[118:119], v[120:121], v[166:167]
	v_add_u32_e32 v120, 0x6fff, v151
	v_mov_b32_e32 v121, v1
	v_lshlrev_b64 v[120:121], 11, v[120:121]
	v_lshlrev_b32_e32 v168, 16, v108
	v_and_b32_e32 v169, 0xffff0000, v108
	v_lshl_add_u64 v[120:121], v[132:133], 0, v[120:121]
	v_lshlrev_b32_e32 v110, 16, v107
	v_and_b32_e32 v111, 0xffff0000, v107
	v_pk_add_f32 v[106:107], v[126:127], v[154:155]
	v_pk_add_f32 v[126:127], v[152:153], v[168:169]
	s_waitcnt vmcnt(3)
	v_mov_b64_e32 v[152:153], v[248:249]
	v_mov_b64_e32 v[154:155], v[250:251]
	v_lshlrev_b32_e32 v170, 16, v109
	v_and_b32_e32 v171, 0xffff0000, v109
	v_pk_add_f32 v[108:109], v[124:125], v[164:165]
	s_waitcnt vmcnt(2)
	v_mov_b64_e32 v[164:165], v[172:173]
	v_mov_b64_e32 v[166:167], v[174:175]
	v_pk_add_f32 v[110:111], v[122:123], v[110:111]
	v_pk_add_f32 v[114:115], v[114:115], v[170:171]
	s_nop 0
	v_lshlrev_b32_e32 v124, 16, v153
	v_and_b32_e32 v125, 0xffff0000, v153
	v_pk_add_f32 v[124:125], v[106:107], v[124:125]
	v_add_u32_e32 v106, 0x77ff, v151
	v_mov_b32_e32 v107, v1
	v_lshlrev_b32_e32 v122, 16, v152
	v_and_b32_e32 v123, 0xffff0000, v152
	s_nop 0
	v_lshlrev_b32_e32 v156, 16, v164
	v_and_b32_e32 v157, 0xffff0000, v164
	v_lshlrev_b32_e32 v164, 16, v165
	v_and_b32_e32 v165, 0xffff0000, v165
	v_lshlrev_b64 v[106:107], 11, v[106:107]
	v_lshlrev_b32_e32 v152, 16, v154
	v_and_b32_e32 v153, 0xffff0000, v154
	v_lshlrev_b32_e32 v154, 16, v155
	v_and_b32_e32 v155, 0xffff0000, v155
	v_pk_add_f32 v[120:121], v[112:113], v[122:123]
	v_pk_add_f32 v[112:113], v[118:119], v[156:157]
	v_pk_add_f32 v[118:119], v[110:111], v[164:165]
	v_lshl_add_u64 v[164:165], v[132:133], 0, v[106:107]
	v_pk_add_f32 v[122:123], v[108:109], v[154:155]
	s_waitcnt vmcnt(1)
	v_mov_b64_e32 v[106:107], v[176:177]
	v_mov_b64_e32 v[108:109], v[178:179]
	v_lshlrev_b32_e32 v168, 16, v166
	v_and_b32_e32 v169, 0xffff0000, v166
	v_pk_add_f32 v[116:117], v[116:117], v[152:153]
	v_pk_add_f32 v[110:111], v[126:127], v[168:169]
	v_lshlrev_b32_e32 v166, 16, v167
	v_and_b32_e32 v167, 0xffff0000, v167
	v_pk_add_f32 v[114:115], v[114:115], v[166:167]
	s_nop 0
	v_lshlrev_b32_e32 v152, 16, v106
	v_and_b32_e32 v153, 0xffff0000, v106
	v_lshlrev_b32_e32 v156, 16, v107
	v_and_b32_e32 v157, 0xffff0000, v107
	v_lshlrev_b32_e32 v126, 16, v108
	v_and_b32_e32 v127, 0xffff0000, v108
	v_lshlrev_b32_e32 v154, 16, v109
	v_and_b32_e32 v155, 0xffff0000, v109
	s_waitcnt vmcnt(0)
	v_mov_b64_e32 v[106:107], v[180:181]
	v_mov_b64_e32 v[108:109], v[182:183]
	v_pk_add_f32 v[156:157], v[124:125], v[156:157]
	v_pk_add_f32 v[152:153], v[120:121], v[152:153]
	v_pk_add_f32 v[124:125], v[122:123], v[154:155]
	v_pk_add_f32 v[116:117], v[116:117], v[126:127]
	s_nop 0
	v_lshlrev_b32_e32 v164, 16, v106
	v_and_b32_e32 v165, 0xffff0000, v106
	v_lshlrev_b32_e32 v106, 16, v107
	v_and_b32_e32 v107, 0xffff0000, v107
	v_lshlrev_b32_e32 v166, 16, v108
	v_and_b32_e32 v167, 0xffff0000, v108
	v_lshlrev_b32_e32 v108, 16, v109
	v_and_b32_e32 v109, 0xffff0000, v109
	v_pk_add_f32 v[120:121], v[118:119], v[106:107]
	v_pk_add_f32 v[122:123], v[112:113], v[164:165]
	v_pk_add_f32 v[106:107], v[114:115], v[108:109]
	v_pk_add_f32 v[110:111], v[110:111], v[166:167]

; __device__ __forceinline__ unsigned cvt_pk_bf16(float lo, float hi) { unsigned r; asm volatile("v_cvt_pk_bf16_f32 %0, %1, %2" : "=v"(r) : "v"(lo), "v"(hi)); return r; }
; __device__ __forceinline__ void norm_phase(const Args& a, LAS unsigned char* lds, int l, int j, int l2, int j2, int nrows, float wgt, int tid, int G) {
;     ...
;         if (l2 < DEPTH) {
;             float ss = 0.f;
; #pragma unroll
;             for (int k = 0; k < 4; ++k) ss += (sv[k][0] * sv[k][0] + sv[k][1] * sv[k][1]) + (sv[k][2] * sv[k][2] + sv[k][3] * sv[k][3]);
;             ss = wave_sum(ss);
;             const float rstd = rsqrtf(ss * (1.0f / DM) + EPSV);
;             f32x4 y[4];
; #pragma unroll
;             for (int k = 0; k < 4; ++k) y[k] = (sv[k] * rstd) * Bv[k] + Cv[k];
;             *(u32x4*)(Y + (size_t)row * DM + cl) = (u32x4){cvt_pk_bf16(y[0][0], y[0][1]), cvt_pk_bf16(y[0][2], y[0][3]), cvt_pk_bf16(y[1][0], y[1][1]), cvt_pk_bf16(y[1][2], y[1][3])};
;             *(u32x4*)(Y + (size_t)row * DM + 512 + cl) = (u32x4){cvt_pk_bf16(y[2][0], y[2][1]), cvt_pk_bf16(y[2][2], y[2][3]), cvt_pk_bf16(y[3][0], y[3][1]), cvt_pk_bf16(y[3][2], y[3][3])};
;         }
.LBB0_580:
	v_mul_f32_e32 v58, v113, v113
	v_mul_f32_e32 v59, v115, v115
	v_fmac_f32_e32 v58, v112, v112
	v_fmac_f32_e32 v59, v114, v114
	v_add_f32_e32 v58, v58, v59
	v_mul_f32_e32 v59, v117, v117
	v_mul_f32_e32 v60, v119, v119
	v_fmac_f32_e32 v59, v116, v116
	v_fmac_f32_e32 v60, v118, v118
	v_add_f32_e32 v59, v59, v60
	v_add_f32_e32 v58, v58, v59
	v_mul_f32_e32 v59, v121, v121
	v_mul_f32_e32 v60, v123, v123
	v_fmac_f32_e32 v59, v120, v120
	v_fmac_f32_e32 v60, v122, v122
	v_add_f32_e32 v59, v59, v60
	v_add_f32_e32 v58, v59, v58
	v_mul_f32_e32 v59, v125, v125
	v_mul_f32_e32 v60, v127, v127
	v_fmac_f32_e32 v59, v124, v124
	v_fmac_f32_e32 v60, v126, v126
	v_add_f32_e32 v59, v59, v60
	v_add_f32_e32 v58, v59, v58
	s_nop 1
	v_add_f32_dpp v58, v58, v58 quad_perm:[1,0,3,2] row_mask:0xf bank_mask:0xf bound_ctrl:1
	s_nop 1
	v_add_f32_dpp v58, v58, v58 quad_perm:[2,3,0,1] row_mask:0xf bank_mask:0xf bound_ctrl:1
	s_nop 1
	v_add_f32_dpp v58, v58, v58 row_half_mirror row_mask:0xf bank_mask:0xf bound_ctrl:1
	s_nop 1
	v_add_f32_dpp v58, v58, v58 row_mirror row_mask:0xf bank_mask:0xf bound_ctrl:1
	v_mov_b32_e32 v59, v58
	s_nop 1
	v_permlane16_swap_b32_e32 v58, v59
	v_add_f32_e32 v58, v58, v59
	v_mov_b32_e32 v59, v58
	s_nop 1
	v_permlane32_swap_b32_e32 v58, v59
	v_add_f32_e32 v58, v58, v59
	v_fmamk_f32 v58, v58, 0x3a800000, v185
	v_mul_f32_e32 v59, 0x4b800000, v58
	v_cmp_gt_f32_e32 vcc, s16, v58
	s_nop 1
	v_cndmask_b32_e32 v58, v58, v59, vcc
	v_rsq_f32_e32 v58, v58
	s_nop 0
	v_mul_f32_e32 v59, 0x45800000, v58
	v_cndmask_b32_e32 v58, v58, v59, vcc
	v_pk_mul_f32 v[62:63], v[114:115], v[58:59] op_sel_hi:[1,0]
	v_pk_mul_f32 v[60:61], v[112:113], v[58:59] op_sel_hi:[1,0]
	s_waitcnt lgkmcnt(7)
	v_pk_fma_f32 v[62:63], v[4:5], v[62:63], v[16:17]
	v_pk_mul_f32 v[64:65], v[116:117], v[58:59] op_sel_hi:[1,0]
	v_pk_mul_f32 v[66:67], v[118:119], v[58:59] op_sel_hi:[1,0]
	v_pk_mul_f32 v[68:69], v[120:121], v[58:59] op_sel_hi:[1,0]
	v_pk_mul_f32 v[70:71], v[122:123], v[58:59] op_sel_hi:[1,0]
	v_pk_mul_f32 v[72:73], v[124:125], v[58:59] op_sel_hi:[1,0]
	v_pk_mul_f32 v[58:59], v[126:127], v[58:59] op_sel_hi:[1,0]
	v_pk_fma_f32 v[60:61], v[2:3], v[60:61], v[14:15]
	s_waitcnt lgkmcnt(0)
	v_pk_fma_f32 v[98:99], v[96:97], v[58:59], v[80:81]
	v_cvt_pk_bf16_f32 v58, v60, v61
	v_cvt_pk_bf16_f32 v59, v62, v63
	v_lshlrev_b64 v[62:63], 11, v[150:151]
	v_pk_fma_f32 v[66:67], v[52:53], v[66:67], v[12:13]
	v_pk_fma_f32 v[64:65], v[50:51], v[64:65], v[10:11]
	v_lshl_add_u64 v[62:63], v[146:147], 0, v[62:63]
	v_cvt_pk_bf16_f32 v60, v64, v65
	v_cvt_pk_bf16_f32 v61, v66, v67
	s_nop 0
	v_pk_fma_f32 v[70:71], v[76:77], v[70:71], v[92:93]
	v_pk_fma_f32 v[68:69], v[74:75], v[68:69], v[90:91]
	v_pk_fma_f32 v[72:73], v[94:95], v[72:73], v[78:79]
	global_store_dwordx4 v[62:63], v[58:61], off
	s_nop 1
	v_cvt_pk_bf16_f32 v58, v68, v69
	v_cvt_pk_bf16_f32 v59, v70, v71
	v_cvt_pk_bf16_f32 v60, v72, v73
	v_cvt_pk_bf16_f32 v61, v98, v99
	global_store_dwordx4 v[62:63], v[58:61], off offset:1024
	s_branch .LBB0_556
